# strategy 4 on the forget-gate phase: waves 0-3 raised to priority 1 from the phase start (reset by the QKV GEMM loop)
# speedup vs baseline: 1.0034x; 1.0016x over previous
; #define LAS __attribute__((address_space(3)))
; #define IDS() int tid__ = threadIdx.x; asm volatile("" : "+v"(tid__)); const int lane = tid__ & 63, wave = __builtin_amdgcn_readfirstlane(tid__ >> 6), gw = blockIdx.x * 8 + wave, gwT = wave * G + blockIdx.x; (void)lane; (void)gw; (void)gwT
; __device__ __forceinline__ void logf_phase(const Args& a, int l, const u64* ssv, LAS unsigned char* lds, int gw, int NGW, int wave, int lane) {
;     asm volatile("" : "+v"(lane));
;     const float* wf = (const float*)(a.ws + WS_WF) + (size_t)l * 8 * DM; float* logf = (float*)(a.ws + WS_LOGF); const bf16_t* hbp = (const bf16_t*)(a.ws + WS_HB);
;     LAS f32x4* wl = (LAS f32x4*)lds;
;     for (int i = wave * 64 + lane; i < 8 * DM / 4; i += 512) wl[i] = *(const f32x4*)(wf + 4 * i);
; __global__ void __launch_bounds__(512, 2) fwd(Args a) {
;     ...
;         if (IN(p0 + 2)) {
;             { IDS(); logf_phase(a, l, ss_b, lds, gw, NGW, wave, lane);
.LBB0_329:
	s_or_b64 exec, exec, s[0:1]
	s_waitcnt lgkmcnt(0)
	s_barrier
	v_readfirstlane_b32 s100, v236
	s_lshr_b32 s100, s100, 6
	s_cmp_ge_u32 s100, 4
	s_cbranch_scc1 .Llogf_prio_skip
	s_setprio 1
.Llogf_prio_skip:
.LBB0_330:
	v_readlane_b32 s16, v252, 18
	v_readlane_b32 s22, v252, 24
	v_readlane_b32 s23, v252, 25
	s_cmp_le_i32 s22, s2
	s_cselect_b64 s[0:1], -1, 0
	s_cmp_lt_i32 s2, s23
	s_cselect_b64 s[6:7], -1, 0
	s_and_b64 s[0:1], s[0:1], s[6:7]
	s_andn2_b64 vcc, exec, s[0:1]
	v_readlane_b32 s17, v252, 19
	v_readlane_b32 s18, v252, 20
	v_readlane_b32 s19, v252, 21
	v_readlane_b32 s20, v252, 22
	v_readlane_b32 s21, v252, 23
	s_cbranch_vccnz .LBB0_436
	v_mov_b32_e32 v0, v236
	s_nop 0
	v_and_b32_e32 v12, 63, v0
	v_readfirstlane_b32 s9, v0
	s_waitcnt lgkmcnt(0)
	v_mov_b32_e32 v4, v12
	s_and_b32 s0, s9, 0xffffffc0
	s_nop 0
	v_add_u32_e32 v0, s0, v4
	s_movk_i32 s0, 0x1000
	v_cmp_gt_i32_e32 vcc, s0, v0
	v_lshlrev_b32_e32 v8, 2, v4
	s_and_saveexec_b64 s[0:1], vcc
	s_cbranch_execz .LBB0_334
	v_readlane_b32 s6, v255, 0
	v_readlane_b32 s7, v255, 1
	s_mov_b32 s17, s7
	s_lshl_b32 s16, s46, 14
	v_writelane_b32 v255, s6, 0
	v_readlane_b32 s2, v254, 5
	v_add_u32_e32 v0, 0xfffffe00, v0
	v_writelane_b32 v255, s7, 1
	s_lshl_b64 s[6:7], s[16:17], 2
	s_add_u32 s16, s2, s6
	v_readlane_b32 s2, v254, 6
	s_addc_u32 s17, s2, s7
	s_lshr_b32 s2, s9, 6
	s_lshl_b32 s6, s2, 10
	s_add_i32 s6, s6, 0
	v_lshl_add_u32 v5, v4, 4, s6
	v_lshl_add_u32 v2, s2, 8, v8
	s_mov_b64 s[18:19], 0
